# MLA (tiles by global_load_lds, barriers behind PV MFMAs): one static s_setprio 1 for waves 4-7 inside the MLA loop (strategy: static priority raise for the younger half, re-tested on the new loop stru
# speedup vs baseline: 1.0157x; 1.0046x over previous
; #define SLOAD() do { vs0 = *(const bf16x8*)(Vh + voff); vs1 = *(const bf16x8*)(Vh + voff + 32u * (unsigned)ldv); \
;     ks0 = *(const bf16x8*)(Kh + koff); ks1 = *(const bf16x8*)(Kh + koff + 32u * (unsigned)ldk); \
;     if constexpr (NR > 0) { kr = *(const bf16x8*)(Krh + kroff); kroff += 64u * 64u; } voff += 64u * (unsigned)ldv; koff += 64u * (unsigned)ldk; } while (0)
; #define SWRITE(b) do { *(bf16x8*)(V_lds + (b) * SHM_V + vst0) = vs0; *(bf16x8*)(V_lds + (b) * SHM_V + vst1) = vs1; const int kc = sc * 2;  \
;     *(bf16x8*)(K_lds + (b) * SHM_K + KSWZ(sr, kc)) = ks0; *(bf16x8*)(K_lds + (b) * SHM_K + KSWZ(32 + sr, kc)) = ks1; \
;     if constexpr (NR > 0) *(bf16x8*)(Kr_lds + (b) * SHM_KR + krst) = kr; } while (0)
; #define SLOAD() do { vs0 = *(const bf16x8*)(Vh + voff); vs1 = *(const bf16x8*)(Vh + voff + 32u * (unsigned)ldv); \
;     ks0 = *(const bf16x8*)(Kh + voff); ks1 = *(const bf16x8*)(Kh + voff + 32u * (unsigned)ldv); \
;     if constexpr (NR > 0) { kr = *(const bf16x8*)(Krh + kroff); kroff += 64u * 64u; } voff += 64u * (unsigned)ldv; } while (0)
; #define SWRITE(b) do { *(bf16x8*)(V_lds + (b) * SHM_V + vst0) = vs0; *(bf16x8*)(V_lds + (b) * SHM_V + vst0 + 8192) = vs1;  \
;     *(bf16x8*)(K_lds + (b) * SHM_K + kst0) = ks0; *(bf16x8*)(K_lds + (b) * SHM_K + kst0 + 8192) = ks1; \
;     if constexpr (NR > 0) *(bf16x8*)(Kr_lds + (b) * SHM_KR + krst) = kr; } while (0)
; #define SWRITE(b) do { *(bf16x8*)(V_lds + (b) * 16384 + vst0) = vs0; *(bf16x8*)(V_lds + (b) * 16384 + vst0 + 8192) = vs1;  \
;     *(v4i32*)(Kn_lds + (b) * 8192 + knst) = kn; if (krw) *(v4i32*)(Kr_lds + (b) * 4096 + krst) = kr; } while (0)
; __device__ __forceinline__ void attn_unit7(const unsigned char* __restrict__ Q8, int ldq, const unsigned char* __restrict__ Kn8, int ldk, const unsigned char* __restrict__ Kr8, ...
;     ...
;   unsigned vtoff = (unsigned)(tid * 16), knoff = (unsigned)(knr * ldk + knc * 16), kroff = (unsigned)(krr * 64 + krc * 16);
;   v4i32 vt, kn, kr;
;     ...
;   f32x16 pA0, pA1, pB0, pB1; float alA, alB; v8i32 p8;
;   SLOAD(); SWRITE(0); __syncthreads();
;   SLOAD();
;   qkt9(pA0, pA1, Kn_lds, Kr_lds, qf, 7.0f - m_reg, r32, hi); partialSM9(pA0, pA1, m_reg, alA, thr_raw);
;   SWRITE(1); __syncthreads();
;   for (int j = 1; j + 1 < NT; j += 2) {
;     SLOAD();
;     qkt9(pB0, pB1, Kn_lds + 8192, Kr_lds + 4096, qf, 7.0f - m_reg, r32, hi);
.Lmla_stag_entry:
	s_setprio 1
	s_add_i32 m0, s98, 0xa800
	s_nop 0
	global_load_lds_dwordx4 v176, s[18:19]
	s_add_i32 m0, s98, 0xc800
	s_nop 0
	global_load_lds_dwordx4 v178, s[16:17]
	s_nop 1
	v_add_u32_e32 v176, 0x2000, v176
	v_add_u32_e32 v178, 0x20000, v178
